# MoBA loops: waves 4-7 raise their priority for the QK MFMAs so the two waves of a SIMD fall out of phase (one in softmax VALU while the other issues MFMA)
# speedup vs baseline: 1.0035x; 1.0035x over previous
.LBB0_298:
	s_cmp_lt_u32 s95, 0x2000
	s_cbranch_scc1 .Lpp1_lo
	s_setprio 2

.LBB0_431:
	s_cmp_lt_u32 s92, 0x2000
	s_cbranch_scc1 .Lpp2_lo
	s_setprio 2

.LBB0_464:
	s_cmp_lt_u32 s91, 0x2000
	s_cbranch_scc1 .Lpp3_lo
	s_setprio 2
